# mem-attention gate loads hoisted (8 in flight instead of 7 serial round trips), gMLP next-index atomic deferred, permlane swaps for the RMS reduction in GEMM1 epilogue, next-item attention loads issue
# speedup vs baseline: 1.1196x; 1.0012x over previous
.LBB0_203:
	v_mov_b32_e32 v181, 1.0
	v_cndmask_b32_e64 v130, 0, 1, s[34:35]
	v_cmp_ne_u32_e64 s[40:41], 1, v130
	s_andn2_b64 vcc, exec, s[34:35]
	v_mov_b32_e32 v180, v181
	v_mov_b32_e32 v185, v181
	v_mov_b32_e32 v184, v181
	v_mov_b32_e32 v189, v181
	v_mov_b32_e32 v188, v181
	v_mov_b32_e32 v193, v181
	v_mov_b32_e32 v192, v181
	v_mov_b32_e32 v169, v181
	v_mov_b32_e32 v168, v181
	v_mov_b32_e32 v183, v181
	v_mov_b32_e32 v182, v181
	v_mov_b32_e32 v187, v181
	v_mov_b32_e32 v186, v181
	v_mov_b32_e32 v191, v181
	v_mov_b32_e32 v190, v181
	v_mov_b32_e32 v175, v181
	v_mov_b32_e32 v174, v181
	v_mov_b32_e32 v173, v181
	v_mov_b32_e32 v172, v181
	v_mov_b32_e32 v163, v181
	v_mov_b32_e32 v162, v181
	v_mov_b32_e32 v161, v181
	v_mov_b32_e32 v160, v181
	v_mov_b32_e32 v165, v181
	v_mov_b32_e32 v164, v181
	v_mov_b32_e32 v167, v181
	v_mov_b32_e32 v166, v181
	v_mov_b32_e32 v171, v181
	v_mov_b32_e32 v170, v181
	v_mov_b32_e32 v177, v181
	v_mov_b32_e32 v176, v181
	s_cbranch_vccnz .LBB0_237
	v_and_b32_e32 v131, 64, v220
	v_xor_b32_e32 v130, 16, v220
	v_add_u32_e32 v132, 64, v131
	v_cmp_lt_i32_e32 vcc, v130, v132
	v_xor_b32_e32 v134, 32, v220
	s_nop 0
	v_cndmask_b32_e32 v130, v220, v130, vcc
	v_lshlrev_b32_e32 v131, 2, v130
	v_mul_f32_e32 v130, v123, v123
	v_fmac_f32_e32 v130, v122, v122
	v_fmac_f32_e32 v130, v124, v124
	v_fmac_f32_e32 v130, v125, v125
	v_fmac_f32_e32 v130, v114, v114
	v_fmac_f32_e32 v130, v115, v115
	v_fmac_f32_e32 v130, v116, v116
	v_fmac_f32_e32 v130, v117, v117
	v_mov_b32_e32 v133, v130
	s_nop 1
	v_permlane16_swap_b32_e32 v133, v130
	v_cmp_lt_i32_e32 vcc, v134, v132
	v_add_f32_e32 v130, v130, v133
	v_cndmask_b32_e32 v132, v220, v134, vcc
	v_lshlrev_b32_e32 v157, 2, v132
	v_mov_b32_e32 v132, v130
	s_nop 1
	v_permlane32_swap_b32_e32 v132, v130
	v_add_f32_e32 v132, v130, v132
	s_and_saveexec_b64 s[34:35], s[4:5]
	ds_write_b32 v221, v132
	s_or_b64 exec, exec, s[34:35]
	v_mul_f32_e32 v130, v107, v107
	v_fmac_f32_e32 v130, v106, v106
	v_fmac_f32_e32 v130, v108, v108
	v_fmac_f32_e32 v130, v109, v109
	v_fmac_f32_e32 v130, v98, v98
	v_fmac_f32_e32 v130, v99, v99
	v_fmac_f32_e32 v130, v100, v100
	v_fmac_f32_e32 v130, v101, v101
	v_mov_b32_e32 v133, v130
	s_nop 1
	v_permlane16_swap_b32_e32 v133, v130
	v_add_f32_e32 v130, v130, v133
	v_mov_b32_e32 v133, v130
	s_nop 1
	v_permlane32_swap_b32_e32 v133, v130
	v_add_f32_e32 v133, v130, v133
	s_and_saveexec_b64 s[34:35], s[4:5]
	ds_write_b32 v221, v133 offset:64
	s_or_b64 exec, exec, s[34:35]
	v_mul_f32_e32 v130, v91, v91
	v_fmac_f32_e32 v130, v90, v90
	v_fmac_f32_e32 v130, v92, v92
	v_fmac_f32_e32 v130, v93, v93
	v_fmac_f32_e32 v130, v82, v82
	v_fmac_f32_e32 v130, v83, v83
	v_fmac_f32_e32 v130, v84, v84
	v_fmac_f32_e32 v130, v85, v85
	v_mov_b32_e32 v134, v130
	s_nop 1
	v_permlane16_swap_b32_e32 v134, v130
	v_add_f32_e32 v130, v130, v134
	v_mov_b32_e32 v134, v130
	s_nop 1
	v_permlane32_swap_b32_e32 v134, v130
	v_add_f32_e32 v168, v130, v134
	s_and_saveexec_b64 s[34:35], s[4:5]
	ds_write_b32 v221, v168 offset:128
	s_or_b64 exec, exec, s[34:35]
	v_mul_f32_e32 v130, v75, v75
	v_fmac_f32_e32 v130, v74, v74
	v_fmac_f32_e32 v130, v76, v76
	v_fmac_f32_e32 v130, v77, v77
	v_fmac_f32_e32 v130, v66, v66
	v_fmac_f32_e32 v130, v67, v67
	v_fmac_f32_e32 v130, v68, v68
	v_fmac_f32_e32 v130, v69, v69
	v_mov_b32_e32 v134, v130
	s_nop 1
	v_permlane16_swap_b32_e32 v134, v130
	v_add_f32_e32 v130, v130, v134
	v_mov_b32_e32 v134, v130
	s_nop 1
	v_permlane32_swap_b32_e32 v134, v130
	v_add_f32_e32 v169, v130, v134
	s_and_saveexec_b64 s[34:35], s[4:5]
	ds_write_b32 v221, v169 offset:192
	s_or_b64 exec, exec, s[34:35]
	v_mul_f32_e32 v130, v59, v59
	v_fmac_f32_e32 v130, v58, v58
	v_fmac_f32_e32 v130, v60, v60
	v_fmac_f32_e32 v130, v61, v61
	v_fmac_f32_e32 v130, v50, v50
	v_fmac_f32_e32 v130, v51, v51
	v_fmac_f32_e32 v130, v52, v52
	v_fmac_f32_e32 v130, v53, v53
	v_mov_b32_e32 v134, v130
	s_nop 1
	v_permlane16_swap_b32_e32 v134, v130
	v_add_f32_e32 v130, v130, v134
	v_mov_b32_e32 v134, v130
	s_nop 1
	v_permlane32_swap_b32_e32 v134, v130
	v_add_f32_e32 v172, v130, v134
	s_and_saveexec_b64 s[34:35], s[4:5]
	ds_write_b32 v254, v172
	s_or_b64 exec, exec, s[34:35]
	v_mul_f32_e32 v130, v43, v43
	v_fmac_f32_e32 v130, v42, v42
	v_fmac_f32_e32 v130, v44, v44
	v_fmac_f32_e32 v130, v45, v45
	v_fmac_f32_e32 v130, v34, v34
	v_fmac_f32_e32 v130, v35, v35
	v_fmac_f32_e32 v130, v36, v36
	v_fmac_f32_e32 v130, v37, v37
	v_mov_b32_e32 v134, v130
	s_nop 1
	v_permlane16_swap_b32_e32 v134, v130
	v_add_f32_e32 v130, v130, v134
	v_mov_b32_e32 v134, v130
	s_nop 1
	v_permlane32_swap_b32_e32 v134, v130
	v_add_f32_e32 v173, v130, v134
	s_and_saveexec_b64 s[34:35], s[4:5]
	ds_write_b32 v221, v173 offset:320
	s_or_b64 exec, exec, s[34:35]
	v_mul_f32_e32 v130, v27, v27
	v_fmac_f32_e32 v130, v26, v26
	v_fmac_f32_e32 v130, v28, v28
	v_fmac_f32_e32 v130, v29, v29
	v_fmac_f32_e32 v130, v18, v18
	v_fmac_f32_e32 v130, v19, v19
	v_fmac_f32_e32 v130, v20, v20
	v_fmac_f32_e32 v130, v21, v21
	v_mov_b32_e32 v134, v130
	s_nop 1
	v_permlane16_swap_b32_e32 v134, v130
	v_add_f32_e32 v130, v130, v134
	v_mov_b32_e32 v134, v130
	s_nop 1
	v_permlane32_swap_b32_e32 v134, v130
	v_add_f32_e32 v174, v130, v134
	s_and_saveexec_b64 s[34:35], s[4:5]
	ds_write_b32 v221, v174 offset:384
	s_or_b64 exec, exec, s[34:35]
	v_mul_f32_e32 v130, v11, v11
	v_fmac_f32_e32 v130, v10, v10
	v_fmac_f32_e32 v130, v12, v12
	v_fmac_f32_e32 v130, v13, v13
	v_fmac_f32_e32 v130, v2, v2
	v_fmac_f32_e32 v130, v3, v3
	v_fmac_f32_e32 v130, v4, v4
	v_fmac_f32_e32 v130, v5, v5
	v_mov_b32_e32 v134, v130
	s_nop 1
	v_permlane16_swap_b32_e32 v134, v130
	v_add_f32_e32 v130, v130, v134
	v_mov_b32_e32 v134, v130
	s_nop 1
	v_permlane32_swap_b32_e32 v134, v130
	v_add_f32_e32 v175, v130, v134
	s_and_saveexec_b64 s[34:35], s[4:5]
	ds_write_b32 v221, v175 offset:448
	s_or_b64 exec, exec, s[34:35]
	v_mul_f32_e32 v130, v127, v127
	v_fmac_f32_e32 v130, v126, v126
	v_fmac_f32_e32 v130, v128, v128
	v_fmac_f32_e32 v130, v129, v129
	v_fmac_f32_e32 v130, v118, v118
	v_fmac_f32_e32 v130, v119, v119
	v_fmac_f32_e32 v130, v120, v120
	v_fmac_f32_e32 v130, v121, v121
	v_mov_b32_e32 v134, v130
	s_nop 1
	v_permlane16_swap_b32_e32 v134, v130
	v_add_f32_e32 v130, v130, v134
	v_mov_b32_e32 v134, v130
	s_nop 1
	v_permlane32_swap_b32_e32 v134, v130
	v_add_f32_e32 v136, v130, v134
	s_and_saveexec_b64 s[34:35], s[4:5]
	ds_write_b32 v208, v136
	s_or_b64 exec, exec, s[34:35]
	v_mul_f32_e32 v130, v111, v111
	v_fmac_f32_e32 v130, v110, v110
	v_fmac_f32_e32 v130, v112, v112
	v_fmac_f32_e32 v130, v113, v113
	v_fmac_f32_e32 v130, v102, v102
	v_fmac_f32_e32 v130, v103, v103
	v_fmac_f32_e32 v130, v104, v104
	v_fmac_f32_e32 v130, v105, v105
	v_mov_b32_e32 v134, v130
	s_nop 1
	v_permlane16_swap_b32_e32 v134, v130
	v_add_f32_e32 v130, v130, v134
	v_mov_b32_e32 v134, v130
	s_nop 1
	v_permlane32_swap_b32_e32 v134, v130
	v_add_f32_e32 v137, v130, v134
	s_and_saveexec_b64 s[34:35], s[4:5]
	ds_write_b32 v221, v137 offset:576
	s_or_b64 exec, exec, s[34:35]
	v_mul_f32_e32 v130, v95, v95
	v_fmac_f32_e32 v130, v94, v94
	v_fmac_f32_e32 v130, v96, v96
	v_fmac_f32_e32 v130, v97, v97
	v_fmac_f32_e32 v130, v86, v86
	v_fmac_f32_e32 v130, v87, v87
	v_fmac_f32_e32 v130, v88, v88
	v_fmac_f32_e32 v130, v89, v89
	v_mov_b32_e32 v134, v130
	s_nop 1
	v_permlane16_swap_b32_e32 v134, v130
	v_add_f32_e32 v130, v130, v134
	v_mov_b32_e32 v134, v130
	s_nop 1
	v_permlane32_swap_b32_e32 v134, v130
	v_add_f32_e32 v158, v130, v134
	s_and_saveexec_b64 s[34:35], s[4:5]
	ds_write_b32 v221, v158 offset:640
	s_or_b64 exec, exec, s[34:35]
	v_mul_f32_e32 v130, v79, v79
	v_fmac_f32_e32 v130, v78, v78
	v_fmac_f32_e32 v130, v80, v80
	v_fmac_f32_e32 v130, v81, v81
	v_fmac_f32_e32 v130, v70, v70
	v_fmac_f32_e32 v130, v71, v71
	v_fmac_f32_e32 v130, v72, v72
	v_fmac_f32_e32 v130, v73, v73
	v_mov_b32_e32 v134, v130
	s_nop 1
	v_permlane16_swap_b32_e32 v134, v130
	v_add_f32_e32 v130, v130, v134
	v_mov_b32_e32 v134, v130
	s_nop 1
	v_permlane32_swap_b32_e32 v134, v130
	v_add_f32_e32 v159, v130, v134
	s_and_saveexec_b64 s[34:35], s[4:5]
	ds_write_b32 v221, v159 offset:704
	s_or_b64 exec, exec, s[34:35]
	v_mul_f32_e32 v130, v63, v63
	v_fmac_f32_e32 v130, v62, v62
	v_fmac_f32_e32 v130, v64, v64
	v_fmac_f32_e32 v130, v65, v65
	v_fmac_f32_e32 v130, v54, v54
	v_fmac_f32_e32 v130, v55, v55
	v_fmac_f32_e32 v130, v56, v56
	v_fmac_f32_e32 v130, v57, v57
	v_mov_b32_e32 v134, v130
	s_nop 1
	v_permlane16_swap_b32_e32 v134, v130
	v_add_f32_e32 v130, v130, v134
	v_mov_b32_e32 v134, v130
	s_nop 1
	v_permlane32_swap_b32_e32 v134, v130
	v_add_f32_e32 v134, v130, v134
	s_and_saveexec_b64 s[34:35], s[4:5]
	ds_write_b32 v198, v134
	s_or_b64 exec, exec, s[34:35]
	v_mul_f32_e32 v130, v47, v47
	v_fmac_f32_e32 v130, v46, v46
	v_fmac_f32_e32 v130, v48, v48
	v_fmac_f32_e32 v130, v49, v49
	v_fmac_f32_e32 v130, v38, v38
	v_fmac_f32_e32 v130, v39, v39
	v_fmac_f32_e32 v130, v40, v40
	v_fmac_f32_e32 v130, v41, v41
	v_mov_b32_e32 v135, v130
	s_nop 1
	v_permlane16_swap_b32_e32 v135, v130
	v_add_f32_e32 v130, v130, v135
	v_mov_b32_e32 v135, v130
	s_nop 1
	v_permlane32_swap_b32_e32 v135, v130
	v_add_f32_e32 v135, v130, v135
	s_and_saveexec_b64 s[34:35], s[4:5]
	ds_write_b32 v221, v135 offset:832
	s_or_b64 exec, exec, s[34:35]
	v_mul_f32_e32 v130, v31, v31
	v_fmac_f32_e32 v130, v30, v30
	v_fmac_f32_e32 v130, v32, v32
	v_fmac_f32_e32 v130, v33, v33
	v_fmac_f32_e32 v130, v22, v22
	v_fmac_f32_e32 v130, v23, v23
	v_fmac_f32_e32 v130, v24, v24
	v_fmac_f32_e32 v130, v25, v25
	v_mov_b32_e32 v160, v130
	s_nop 1
	v_permlane16_swap_b32_e32 v160, v130
	v_add_f32_e32 v130, v130, v160
	v_mov_b32_e32 v160, v130
	s_nop 1
	v_permlane32_swap_b32_e32 v160, v130
	v_add_f32_e32 v130, v130, v160
	s_and_saveexec_b64 s[34:35], s[4:5]
	ds_write_b32 v221, v130 offset:896
	s_or_b64 exec, exec, s[34:35]
	v_mul_f32_e32 v160, v15, v15
	v_fmac_f32_e32 v160, v14, v14
	v_fmac_f32_e32 v160, v16, v16
	v_fmac_f32_e32 v160, v17, v17
	v_fmac_f32_e32 v160, v6, v6
	v_fmac_f32_e32 v160, v7, v7
	v_fmac_f32_e32 v160, v8, v8
	v_fmac_f32_e32 v160, v9, v9
	v_mov_b32_e32 v131, v160
	s_nop 1
	v_permlane16_swap_b32_e32 v131, v160
	v_add_f32_e32 v131, v160, v131
	v_mov_b32_e32 v157, v131
	s_nop 1
	v_permlane32_swap_b32_e32 v157, v131
	v_add_f32_e32 v131, v131, v157
	s_and_saveexec_b64 s[34:35], s[4:5]
	ds_write_b32 v196, v131
	s_or_b64 exec, exec, s[34:35]
	v_lshl_add_u64 v[160:161], s[42:43], 0, v[146:147]
	v_mov_b32_e32 v157, v147
	v_lshl_add_u64 v[160:161], v[160:161], 0, v[156:157]
	v_bfe_u32 v157, v0, 7, 1
	v_mul_u32_u24_e32 v157, s70, v157
	v_lshlrev_b32_e32 v162, 2, v157
	v_mov_b32_e32 v163, v147
	v_lshl_add_u64 v[170:171], v[160:161], 0, v[162:163]
	s_waitcnt vmcnt(0) lgkmcnt(0)
	s_barrier
	global_load_dwordx4 v[160:163], v[170:171], off offset:16
	global_load_dwordx4 v[176:179], v[170:171], off
	s_mov_b32 s14, 0x358637bd
	s_lshl_b32 s70, s70, 3
	v_lshl_add_u64 v[170:171], v[170:171], 0, s[70:71]
	s_waitcnt vmcnt(1)
	v_pk_mul_f32 v[162:163], s[30:31], v[162:163] op_sel_hi:[0,1]
	s_waitcnt vmcnt(0)
	v_pk_mul_f32 v[166:167], v[176:177], s[30:31] op_sel_hi:[1,0]
	ds_read2_b32 v[176:177], v211 offset1:16
	v_pk_mul_f32 v[164:165], v[178:179], s[30:31] op_sel_hi:[1,0]
	v_pk_mul_f32 v[160:161], s[30:31], v[160:161] op_sel_hi:[0,1]
	s_waitcnt lgkmcnt(0)
	v_pk_add_f32 v[176:177], v[132:133], v[176:177]
	v_mov_b64_e32 v[132:133], s[14:15]
	v_pk_fma_f32 v[176:177], v[176:177], s[8:9], v[132:133] op_sel_hi:[1,0,0]
	s_nop 0
	v_mul_f32_e32 v157, 0x4b800000, v176
	v_cmp_gt_f32_e64 s[42:43], s11, v176
	v_cmp_gt_f32_e32 vcc, s11, v177
	s_nop 0
	v_cndmask_b32_e64 v157, v176, v157, s[42:43]
	v_rsq_f32_e32 v176, v157
	v_mul_f32_e32 v157, 0x4b800000, v177
	v_cndmask_b32_e32 v157, v177, v157, vcc
	v_rsq_f32_e32 v177, v157
	s_nop 0
	v_pk_mul_f32 v[178:179], v[176:177], s[10:11] op_sel_hi:[1,0]
	s_nop 0
	v_cndmask_b32_e64 v190, v176, v178, s[42:43]
	v_cndmask_b32_e32 v191, v177, v179, vcc
	ds_read2_b32 v[176:177], v211 offset0:32 offset1:48
	s_waitcnt lgkmcnt(0)
	v_pk_add_f32 v[168:169], v[168:169], v[176:177]
	s_nop 0
	v_pk_fma_f32 v[168:169], v[168:169], s[8:9], v[132:133] op_sel_hi:[1,0,0]
	s_nop 0
	v_mul_f32_e32 v157, 0x4b800000, v168
	v_cmp_gt_f32_e64 s[42:43], s11, v168
	v_cmp_gt_f32_e32 vcc, s11, v169
	s_nop 0
	v_cndmask_b32_e64 v157, v168, v157, s[42:43]
	v_rsq_f32_e32 v168, v157
	v_mul_f32_e32 v157, 0x4b800000, v169
	v_cndmask_b32_e32 v157, v169, v157, vcc
	v_rsq_f32_e32 v169, v157
	s_nop 0
	v_pk_mul_f32 v[176:177], v[168:169], s[10:11] op_sel_hi:[1,0]
	s_nop 0
	v_cndmask_b32_e64 v186, v168, v176, s[42:43]
	v_cndmask_b32_e32 v187, v169, v177, vcc
	ds_read_b32 v168, v212
	ds_read2_b32 v[176:177], v211 offset0:80 offset1:96
	ds_read2_b32 v[178:179], v211 offset0:112 offset1:144
	s_waitcnt lgkmcnt(1)
	v_mov_b32_e32 v169, v176
	v_pk_add_f32 v[168:169], v[172:173], v[168:169]
	s_nop 0
	v_pk_fma_f32 v[168:169], v[168:169], s[8:9], v[132:133] op_sel_hi:[1,0,0]
	s_nop 0
	v_mul_f32_e32 v157, 0x4b800000, v168
	v_cmp_gt_f32_e64 s[42:43], s11, v168
	v_cmp_gt_f32_e32 vcc, s11, v169
	s_nop 0
	v_cndmask_b32_e64 v157, v168, v157, s[42:43]
	v_rsq_f32_e32 v168, v157
	v_mul_f32_e32 v157, 0x4b800000, v169
	v_cndmask_b32_e32 v157, v169, v157, vcc
	v_rsq_f32_e32 v169, v157
	s_nop 0
	v_pk_mul_f32 v[172:173], v[168:169], s[10:11] op_sel_hi:[1,0]
	s_nop 0
	v_cndmask_b32_e64 v182, v168, v172, s[42:43]
	v_cndmask_b32_e32 v183, v169, v173, vcc
	v_mov_b32_e32 v168, v177
	s_waitcnt lgkmcnt(0)
	v_mov_b32_e32 v169, v178
	v_pk_add_f32 v[168:169], v[174:175], v[168:169]
	s_nop 0
	v_pk_fma_f32 v[168:169], v[168:169], s[8:9], v[132:133] op_sel_hi:[1,0,0]
	s_nop 0
	v_mul_f32_e32 v157, 0x4b800000, v168
	v_cmp_gt_f32_e64 s[42:43], s11, v168
	v_cmp_gt_f32_e32 vcc, s11, v169
	s_nop 0
	v_cndmask_b32_e64 v157, v168, v157, s[42:43]
	v_rsq_f32_e32 v168, v157
	v_mul_f32_e32 v157, 0x4b800000, v169
	v_cndmask_b32_e32 v157, v169, v157, vcc
	v_rsq_f32_e32 v169, v157
	s_nop 0
	v_pk_mul_f32 v[172:173], v[168:169], s[10:11] op_sel_hi:[1,0]
	s_nop 0
	v_cndmask_b32_e64 v168, v168, v172, s[42:43]
	v_cndmask_b32_e32 v169, v169, v173, vcc
	global_load_dwordx4 v[192:195], v[170:171], off offset:16
	s_nop 0
	global_load_dwordx4 v[170:173], v[170:171], off
	ds_read_b32 v178, v213
	s_waitcnt lgkmcnt(0)
	v_pk_add_f32 v[136:137], v[136:137], v[178:179]
	s_nop 0
	v_pk_fma_f32 v[136:137], v[136:137], s[8:9], v[132:133] op_sel_hi:[1,0,0]
	s_waitcnt vmcnt(1)
	v_pk_mul_f32 v[176:177], s[30:31], v[192:193] op_sel_hi:[0,1]
	v_mul_f32_e32 v157, 0x4b800000, v136
	v_cmp_gt_f32_e64 s[42:43], s11, v136
	v_cmp_gt_f32_e32 vcc, s11, v137
	s_waitcnt vmcnt(0)
	v_pk_mul_f32 v[174:175], s[30:31], v[172:173] op_sel_hi:[0,1]
	v_cndmask_b32_e64 v136, v136, v157, s[42:43]
	v_mul_f32_e32 v157, 0x4b800000, v137
	v_cndmask_b32_e32 v137, v137, v157, vcc
	v_rsq_f32_e32 v136, v136
	v_rsq_f32_e32 v137, v137
	v_pk_mul_f32 v[172:173], s[30:31], v[170:171] op_sel_hi:[0,1]
	v_pk_mul_f32 v[170:171], s[30:31], v[194:195] op_sel_hi:[0,1]
	v_pk_mul_f32 v[178:179], v[136:137], s[10:11] op_sel_hi:[1,0]
	s_nop 0
	v_cndmask_b32_e64 v192, v136, v178, s[42:43]
	v_cndmask_b32_e32 v193, v137, v179, vcc
	ds_read2_b32 v[136:137], v211 offset0:160 offset1:176
	s_waitcnt lgkmcnt(0)
	v_pk_add_f32 v[136:137], v[158:159], v[136:137]
	s_nop 0
	v_pk_fma_f32 v[136:137], v[136:137], s[8:9], v[132:133] op_sel_hi:[1,0,0]
	s_nop 0
	v_mul_f32_e32 v157, 0x4b800000, v136
	v_cmp_gt_f32_e64 s[42:43], s11, v136
	v_cmp_gt_f32_e32 vcc, s11, v137
	s_nop 0
	v_cndmask_b32_e64 v136, v136, v157, s[42:43]
	v_mul_f32_e32 v157, 0x4b800000, v137
	v_cndmask_b32_e32 v137, v137, v157, vcc
	v_rsq_f32_e32 v136, v136
	v_rsq_f32_e32 v137, v137
	s_nop 0
	v_pk_mul_f32 v[158:159], v[136:137], s[10:11] op_sel_hi:[1,0]
	s_nop 0
	v_cndmask_b32_e64 v188, v136, v158, s[42:43]
	v_cndmask_b32_e32 v189, v137, v159, vcc
	ds_read_b32 v158, v214
	ds_read2_b32 v[136:137], v211 offset0:208 offset1:224
	s_waitcnt lgkmcnt(0)
	v_mov_b32_e32 v159, v136
	v_pk_add_f32 v[134:135], v[134:135], v[158:159]
	s_nop 0
	v_pk_fma_f32 v[134:135], v[134:135], s[8:9], v[132:133] op_sel_hi:[1,0,0]
	s_nop 0
	v_mul_f32_e32 v136, 0x4b800000, v134
	v_cmp_gt_f32_e64 s[42:43], s11, v134
	v_cmp_gt_f32_e32 vcc, s11, v135
	s_nop 0
	v_cndmask_b32_e64 v134, v134, v136, s[42:43]
	v_mul_f32_e32 v136, 0x4b800000, v135
	v_cndmask_b32_e32 v135, v135, v136, vcc
	v_rsq_f32_e32 v134, v134
	v_rsq_f32_e32 v135, v135
	s_nop 0
	v_pk_mul_f32 v[158:159], v[134:135], s[10:11] op_sel_hi:[1,0]
	s_nop 0
	v_cndmask_b32_e32 v185, v135, v159, vcc
	ds_read_b32 v135, v215
	v_cndmask_b32_e64 v184, v134, v158, s[42:43]
	v_mov_b32_e32 v134, v137
	s_waitcnt lgkmcnt(0)
	v_pk_add_f32 v[130:131], v[130:131], v[134:135]
	s_nop 0
	v_pk_fma_f32 v[130:131], v[130:131], s[8:9], v[132:133] op_sel_hi:[1,0,0]
	s_nop 0
	v_mul_f32_e32 v132, 0x4b800000, v130
	v_cmp_gt_f32_e64 s[42:43], s11, v130
	v_cmp_gt_f32_e32 vcc, s11, v131
	s_nop 0
	v_cndmask_b32_e64 v130, v130, v132, s[42:43]
	v_mul_f32_e32 v132, 0x4b800000, v131
	v_cndmask_b32_e32 v131, v131, v132, vcc
	v_rsq_f32_e32 v130, v130
	v_rsq_f32_e32 v131, v131
	s_nop 0
	v_pk_mul_f32 v[132:133], v[130:131], s[10:11] op_sel_hi:[1,0]
	s_nop 0
	v_cndmask_b32_e64 v180, v130, v132, s[42:43]
	v_cndmask_b32_e32 v181, v131, v133, vcc

.LBB0_347:
	s_ashr_i32 s9, s6, 4
	s_mul_hi_i32 s10, s9, 0x55555556
	s_lshr_b32 s11, s10, 31
	s_add_i32 s10, s10, s11
	s_and_b32 s7, s6, 15
	s_mul_i32 s10, s10, 3
	s_mul_hi_i32 s6, s6, 0x2aaaaaab
	s_sub_i32 s48, s9, s10
	s_lshr_b32 s9, s6, 31
	s_ashr_i32 s6, s6, 3
	s_add_i32 s6, s6, s9
	s_lshl_b32 s19, s48, 1
	s_and_b32 s49, s6, 7
	s_ashr_i32 s6, s6, 3
	s_bfm_b32 s9, s19, 0
	s_lshr_b32 s34, s7, s19
	s_and_b32 s9, s9, s7
	s_ashr_i32 s7, s6, 31
	s_lshl_b32 s10, s34, 8
	s_mov_b32 s11, s15
	s_lshl_b32 s28, 1, s19
	s_lshl_b64 s[6:7], s[6:7], 12
	s_lshl_b64 s[10:11], s[10:11], s19
	s_mov_b32 s29, s15
	s_add_u32 s6, s10, s6
	s_addc_u32 s31, s11, s7
	s_or_b32 s30, s6, s9
	s_lshl_b64 s[6:7], s[28:29], 7
	s_sub_u32 s10, s30, s6
	s_subb_u32 s11, s31, s7
	s_lshl_b64 s[6:7], 0xd00, s19
	s_mulk_i32 s11, 0xd00
	s_mul_hi_u32 s19, s10, 0xd00
	s_lshl_b32 s9, s49, 6
	s_add_i32 s19, s19, s11
	s_mulk_i32 s10, 0xd00
	s_add_u32 s10, s10, s9
	s_addc_u32 s11, s19, 0
	v_mov_b32_e32 v1, v0
	s_cmp_eq_u32 s34, 0
	s_cselect_b32 s29, 0x80, 0
	s_lshl_b32 s95, s6, 1
	s_lshl_b64 s[96:97], s[10:11], 1
	s_add_u32 s96, s12, s96
	s_addc_u32 s97, s13, s97
	s_mul_i32 s98, s31, 0x1a00
	s_mul_hi_u32 s99, s30, 0x1a00
	s_add_i32 s99, s99, s98
	s_mul_i32 s98, s30, 0x1a00
	s_add_u32 s98, s12, s98
	s_addc_u32 s99, s13, s99
	s_lshl_b32 s9, s9, 1
	s_add_u32 s98, s98, s9
	s_addc_u32 s99, s99, 0
	s_mov_b32 s94, 1
	s_branch .LBB0_361
.LBB0_360:
	s_mov_b32 s94, 0
	v_mov_b64_e32 v[100:101], v[80:81]
	v_mov_b64_e32 v[96:97], v[84:85]
	v_mov_b64_e32 v[92:93], v[72:73]
	v_mov_b64_e32 v[88:89], v[76:77]
	v_mov_b64_e32 v[98:99], v[78:79]
	v_mov_b64_e32 v[94:95], v[82:83]
	v_mov_b64_e32 v[90:91], v[70:71]
	v_mov_b64_e32 v[86:87], v[74:75]
	s_mov_b32 s49, s16
	s_mov_b32 s29, s17
	s_mov_b32 s48, s18
	s_mov_b64 s[30:31], s[20:21]
	s_mov_b32 s28, s14
.LBB0_361:
	v_lshrrev_b32_e32 v15, 6, v0
	v_and_b32_e32 v16, 15, v0
	v_bfe_u32 v148, v0, 4, 2
	v_readfirstlane_b32 s92, v15
	v_lshl_or_b32 v17, v15, 5, v16
	v_lshlrev_b32_e32 v146, 2, v148
	v_sub_u32_e32 v14, v16, v146
	v_mov_b32_e32 v15, 0x90
	v_mul_u32_u24_e32 v194, v17, v15
	v_lshl_add_u32 v194, v148, 4, v194
	v_add_u32_e32 v194, 16, v194
	v_lshrrev_b32_e32 v195, 2, v16
	v_add_u32_e32 v195, v195, v146
	v_lshl_add_u32 v195, s92, 5, v195
	v_mul_u32_u24_e32 v195, v195, v15
	v_and_b32_e32 v16, 3, v0
	v_lshl_add_u32 v195, v16, 3, v195
	v_add_u32_e32 v195, 0xd810, v195
	ds_read_b128 v[178:181], v194 offset:0
	ds_read_b128 v[182:185], v194 offset:64
	ds_read_b128 v[186:189], v194 offset:2304
	ds_read_b128 v[190:193], v194 offset:2368
	ds_read_b64_tr_b16 v[200:201], v195 offset:0
	ds_read_b64_tr_b16 v[202:203], v195 offset:2304
	ds_read_b64_tr_b16 v[204:205], v195 offset:32
	ds_read_b64_tr_b16 v[206:207], v195 offset:2336
	ds_read_b64_tr_b16 v[208:209], v195 offset:64
	ds_read_b64_tr_b16 v[210:211], v195 offset:2368
	ds_read_b64_tr_b16 v[212:213], v195 offset:96
	ds_read_b64_tr_b16 v[214:215], v195 offset:2400
	v_lshrrev_b32_e32 v15, 3, v0
	v_and_b32_e32 v16, 7, v0
	v_lshlrev_b32_e32 v16, 4, v16
	v_mad_u32_u24 v196, v15, s95, v16
	v_and_b32_e32 v16, 48, v0
	v_mad_u32_u24 v198, v17, s95, v16
	s_lshl_b32 s60, s95, 6
	s_lshl_b32 s61, s95, 4
	s_sub_i32 s93, 4, s92
	s_max_i32 s93, s93, 0
	s_cmp_eq_u32 s17, 0
	s_cselect_b32 s93, 0, s93
	v_cmp_le_i32_e64 s[76:77], v14, 0
	v_cmp_le_i32_e64 s[78:79], v14, 1
	v_cmp_le_i32_e64 s[80:81], v14, 2
	v_cmp_le_i32_e64 s[82:83], v14, 3
	v_cmp_ge_i32_e64 s[84:85], v14, 0
	v_cmp_ge_i32_e64 s[86:87], v14, 1
	v_cmp_ge_i32_e64 s[88:89], v14, 2
	v_cmp_ge_i32_e64 s[90:91], v14, 3
	v_mov_b32_e32 v10, 0x3f803f80
	v_mov_b32_e32 v11, v10
	v_mov_b32_e32 v12, v10
	v_mov_b32_e32 v13, v10
	v_mov_b32_e32 v138, 0
	v_mov_b32_e32 v139, 0
	v_mov_b32_e32 v140, 0
	v_mov_b32_e32 v141, 0
	v_mov_b32_e32 v118, 0
	v_mov_b32_e32 v119, 0
	v_mov_b32_e32 v120, 0
	v_mov_b32_e32 v121, 0
	v_mov_b32_e32 v134, 0
	v_mov_b32_e32 v135, 0
	v_mov_b32_e32 v136, 0
	v_mov_b32_e32 v137, 0
	v_mov_b32_e32 v130, 0
	v_mov_b32_e32 v131, 0
	v_mov_b32_e32 v132, 0
	v_mov_b32_e32 v133, 0
	v_mov_b32_e32 v126, 0
	v_mov_b32_e32 v127, 0
	v_mov_b32_e32 v128, 0
	v_mov_b32_e32 v129, 0
	v_mov_b32_e32 v122, 0
	v_mov_b32_e32 v123, 0
	v_mov_b32_e32 v124, 0
	v_mov_b32_e32 v125, 0
	v_mov_b32_e32 v114, 0
	v_mov_b32_e32 v115, 0
	v_mov_b32_e32 v116, 0
	v_mov_b32_e32 v117, 0
	v_mov_b32_e32 v106, 0
	v_mov_b32_e32 v107, 0
	v_mov_b32_e32 v108, 0
	v_mov_b32_e32 v109, 0
	v_mov_b32_e32 v110, 0
	v_mov_b32_e32 v111, 0
	v_mov_b32_e32 v112, 0
	v_mov_b32_e32 v113, 0
	v_mov_b32_e32 v102, 0
	v_mov_b32_e32 v103, 0
	v_mov_b32_e32 v104, 0
	v_mov_b32_e32 v105, 0
	s_waitcnt lgkmcnt(8)
	v_mfma_f32_16x16x32_bf16 v[150:153], v[178:181], v[74:77], v[66:69]
	v_mfma_f32_16x16x32_bf16 v[154:157], v[186:189], v[74:77], v[66:69]
	v_mfma_f32_16x16x32_bf16 v[162:165], v[186:189], v[82:85], v[66:69]
	v_mfma_f32_16x16x32_bf16 v[150:153], v[182:185], v[70:73], v[150:153]
	v_mfma_f32_16x16x32_bf16 v[154:157], v[190:193], v[70:73], v[154:157]
	v_mfma_f32_16x16x32_bf16 v[162:165], v[190:193], v[78:81], v[162:165]
	s_waitcnt lgkmcnt(0)
	ds_read_b128 v[178:181], v194 offset:4608
	ds_read_b128 v[182:185], v194 offset:4672
	ds_read_b128 v[186:189], v194 offset:6912
	ds_read_b128 v[190:193], v194 offset:6976
	ds_read_b64_tr_b16 v[216:217], v195 offset:4608
	ds_read_b64_tr_b16 v[218:219], v195 offset:6912
	ds_read_b64_tr_b16 v[220:221], v195 offset:4640
	ds_read_b64_tr_b16 v[222:223], v195 offset:6944
	ds_read_b64_tr_b16 v[224:225], v195 offset:4672
	ds_read_b64_tr_b16 v[226:227], v195 offset:6976
	ds_read_b64_tr_b16 v[228:229], v195 offset:4704
	ds_read_b64_tr_b16 v[230:231], v195 offset:7008
.Lattn_blk0:
	s_cmp_eq_u32 s94, 0
	s_cbranch_scc1 .Lattn_ldskip0lo
	s_cmp_lt_u32 s92, 4
	s_cbranch_scc0 .Lattn_ldskip0lo
	s_cmp_eq_u32 s29, 0
	s_cbranch_scc0 .Lattn_ldadv0lo_0
	global_load_dwordx4 v[22:25], v196, s[96:97] offset:2560
	global_load_dwordx4 v[18:21], v196, s[96:97] offset:3584
.Lattn_ldadv0lo_0:
	s_add_u32 s96, s96, s60
	s_addc_u32 s97, s97, 0
	s_cmp_eq_u32 s29, 0
	s_cbranch_scc0 .Lattn_ldadv0lo_1
	global_load_dwordx4 v[30:33], v196, s[96:97] offset:2560
	global_load_dwordx4 v[26:29], v196, s[96:97] offset:3584
.Lattn_ldadv0lo_1:
	s_add_u32 s96, s96, s60
	s_addc_u32 s97, s97, 0
	global_load_dwordx4 v[38:41], v196, s[96:97] offset:2560
	global_load_dwordx4 v[34:37], v196, s[96:97] offset:3584
	s_add_u32 s96, s96, s60
	s_addc_u32 s97, s97, 0
.Lattn_ldskip0lo:
	s_cmp_eq_u32 s94, 0
	s_cbranch_scc1 .Lattn_ldskip0hi
	s_cmp_lt_u32 s92, 4
	s_cbranch_scc1 .Lattn_ldskip0hi
	s_cmp_eq_u32 s29, 0
	s_cbranch_scc0 .Lattn_ldadv0hi_0
	global_load_dwordx4 v[22:25], v196, s[96:97] offset:2560
	global_load_dwordx4 v[18:21], v196, s[96:97] offset:3584

.Lattn_end0:
.Lattn_blk1:
	s_cmp_eq_u32 s94, 0
	s_cbranch_scc1 .Lattn_ldskip1lo
	s_cmp_lt_u32 s92, 4
	s_cbranch_scc0 .Lattn_ldskip1lo
	global_load_dwordx4 v[46:49], v196, s[96:97] offset:2560
	global_load_dwordx4 v[42:45], v196, s[96:97] offset:3584
	s_add_u32 s96, s96, s60
	s_addc_u32 s97, s97, 0
	global_load_dwordx4 v[54:57], v196, s[96:97] offset:2560
	global_load_dwordx4 v[50:53], v196, s[96:97] offset:3584
	s_add_u32 s96, s96, s60
	s_addc_u32 s97, s97, 0
	global_load_dwordx4 v[62:65], v196, s[96:97] offset:2560
	global_load_dwordx4 v[58:61], v196, s[96:97] offset:3584
	s_add_u32 s96, s96, s60
	s_addc_u32 s97, s97, 0
	global_load_dwordx4 v[86:89], v198, s[98:99] offset:1536
	global_load_dwordx4 v[90:93], v198, s[98:99] offset:1600
	s_add_u32 s98, s98, s61
	s_addc_u32 s99, s99, 0
	global_load_dwordx4 v[94:97], v198, s[98:99] offset:1536
	global_load_dwordx4 v[98:101], v198, s[98:99] offset:1600
.Lattn_ldskip1lo:
	s_cmp_eq_u32 s94, 0
	s_cbranch_scc1 .Lattn_ldskip1hi
	s_cmp_lt_u32 s92, 4
	s_cbranch_scc1 .Lattn_ldskip1hi
	global_load_dwordx4 v[46:49], v196, s[96:97] offset:2560
	global_load_dwordx4 v[42:45], v196, s[96:97] offset:3584
	s_add_u32 s96, s96, s60
	s_addc_u32 s97, s97, 0
	global_load_dwordx4 v[54:57], v196, s[96:97] offset:2560
	global_load_dwordx4 v[50:53], v196, s[96:97] offset:3584
	s_add_u32 s96, s96, s60
	s_addc_u32 s97, s97, 0
	global_load_dwordx4 v[62:65], v196, s[96:97] offset:2560
	global_load_dwordx4 v[58:61], v196, s[96:97] offset:3584
	s_add_u32 s96, s96, s60
	s_addc_u32 s97, s97, 0
	global_load_dwordx4 v[86:89], v198, s[98:99] offset:1536
	global_load_dwordx4 v[90:93], v198, s[98:99] offset:1600
	s_add_u32 s98, s98, s61
	s_addc_u32 s99, s99, 0
	global_load_dwordx4 v[94:97], v198, s[98:99] offset:1536
	global_load_dwordx4 v[98:101], v198, s[98:99] offset:1600

.LBB0_382:
	v_mov_b32_e32 v47, 0
	v_mov_b32_e32 v51, v0
	s_and_b32 s18, s14, 3
	s_ashr_i32 s16, s14, 7
	s_lshl_b32 s14, s14, 5
	v_ashrrev_i32_e32 v2, 2, v51
	s_ashr_i32 s17, s16, 31
	s_and_b32 s14, s14, 0xf80
	v_bfi_b32 v2, -16, v2, v51
	s_lshl_b32 s19, s18, 15
	s_add_u32 s20, s10, s19
	v_ashrrev_i32_e32 v3, 31, v2
	v_lshrrev_b32_e32 v6, 1, v51
	s_addc_u32 s21, s11, 0
	v_lshlrev_b64 v[4:5], 8, v[2:3]
	v_and_b32_e32 v62, 24, v6
	v_lshl_add_u64 v[4:5], s[20:21], 0, v[4:5]
	v_lshlrev_b32_e32 v42, 1, v62
	s_lshl_b64 s[16:17], s[16:17], 12
	v_lshl_add_u64 v[4:5], v[4:5], 0, v[42:43]
	s_or_b32 s16, s16, s14
	s_lshl_b32 s14, s18, 7
	global_load_dwordx4 v[38:41], v[4:5], off
	global_load_dwordx4 v[34:37], v[4:5], off offset:64
	global_load_dwordx4 v[22:25], v[4:5], off offset:128
	global_load_dwordx4 v[10:13], v[4:5], off offset:192
	v_add_u32_e32 v4, s14, v2
	v_ashrrev_i32_e32 v5, 31, v4
	v_lshl_add_u64 v[4:5], v[4:5], 2, s[12:13]
	global_load_dword v46, v[4:5], off
	v_and_b32_e32 v50, 16, v51
	v_lshrrev_b32_e32 v4, 2, v51
	v_ashrrev_i32_e32 v58, 3, v51
	v_and_or_b32 v14, v4, 8, v50
	v_lshlrev_b32_e32 v4, 4, v51
	v_ashrrev_i32_e32 v59, 31, v58
	v_and_b32_e32 v52, 0x70, v4
	v_lshl_add_u64 v[4:5], s[16:17], 0, v[58:59]
	v_mad_u64_u32 v[6:7], s[20:21], v4, s3, v[44:45]
	v_mad_i32_i24 v7, v5, s3, v7
	v_lshl_add_u64 v[4:5], v[6:7], 0, s[14:15]
	v_add_u32_e32 v6, 0x200, v51
	v_ashrrev_i32_e32 v60, 3, v6
	v_ashrrev_i32_e32 v61, 31, v60
	v_lshl_add_u64 v[6:7], s[16:17], 0, v[60:61]
	v_lshl_add_u64 v[48:49], s[16:17], 0, v[2:3]
	v_mad_u64_u32 v[8:9], s[16:17], v6, s3, v[44:45]
	v_lshlrev_b64 v[2:3], 9, v[48:49]
	v_mov_b32_e32 v53, v43
	v_mad_i32_i24 v9, v7, s3, v9
	v_lshl_add_u64 v[2:3], s[6:7], 0, v[2:3]
	v_lshl_add_u64 v[4:5], v[4:5], 0, v[52:53]
	v_lshl_add_u64 v[6:7], v[8:9], 0, s[14:15]
	v_lshl_add_u64 v[6:7], v[6:7], 0, v[52:53]
	global_load_dwordx4 v[18:21], v[4:5], off offset:512
	global_load_dwordx4 v[54:57], v[6:7], off offset:512
	v_lshl_add_u64 v[2:3], v[2:3], 0, s[14:15]
	v_lshlrev_b32_e32 v42, 1, v14
	v_lshl_add_u64 v[14:15], v[2:3], 0, v[42:43]
	global_load_dwordx4 v[6:9], v[14:15], off
	global_load_dwordx4 v[2:5], v[14:15], off offset:64
	s_and_saveexec_b64 s[60:61], s[44:45]
	s_cbranch_execz .Lg_noatom
	v_mov_b32_e32 v67, 1
	global_atomic_add v67, v43, v67, s[8:9] sc0
.Lg_noatom:
	s_or_b64 exec, exec, s[60:61]
	v_bfe_u32 v59, v51, 2, 2
	v_ashrrev_i32_e32 v53, 7, v51
	v_add_u32_e32 v52, 16, v52
	v_mov_b32_e32 v26, v43
	v_mov_b32_e32 v27, v43
	v_mov_b32_e32 v28, v43
	v_mov_b32_e32 v29, v43
	v_lshlrev_b32_e32 v51, 2, v51
	v_or_b32_e32 v62, v62, v59
	v_mad_u64_u32 v[58:59], s[16:17], v58, s22, v[52:53]
	v_mov_b64_e32 v[32:33], v[28:29]
	v_mov_b64_e32 v[14:15], v[26:27]
	v_and_b32_e32 v51, 12, v51
	v_mad_u64_u32 v[60:61], s[16:17], v60, s22, v[52:53]
	v_mov_b64_e32 v[30:31], v[26:27]
	v_mov_b64_e32 v[16:17], v[28:29]
	v_cmp_lt_i32_e32 vcc, -1, v53
	v_lshlrev_b32_e32 v51, 1, v51
	v_mul_u32_u24_e32 v52, 0x90, v62
	s_cmp_lg_u64 s[44:45], 0
	s_cbranch_scc1 .Lg_w0_a
	s_waitcnt vmcnt(3)
	s_branch .Lg_j_a
.Lg_w0_a:
	s_waitcnt vmcnt(4)
.Lg_j_a:
	ds_write_b128 v58, v[18:21]
	s_cmp_lg_u64 s[44:45], 0
	s_cbranch_scc1 .Lg_w0_b
	s_waitcnt vmcnt(2)
	s_branch .Lg_j_b
.Lg_w0_b:
	s_waitcnt vmcnt(3)
.Lg_j_b:
	ds_write_b128 v60, v[54:57]
	v_mov_b64_e32 v[18:19], v[26:27]
	v_mov_b64_e32 v[20:21], v[28:29]
	s_waitcnt lgkmcnt(0)
	s_barrier
	s_and_saveexec_b64 s[16:17], vcc
	s_cbranch_execz .LBB0_390
	v_add3_u32 v26, 16, v52, v51
	ds_read_b64_tr_b16 v[14:15], v26
	ds_read_b64_tr_b16 v[16:17], v26 offset:576
	ds_read_b64_tr_b16 v[20:21], v26 offset:608
	ds_read_b64_tr_b16 v[18:19], v26 offset:32
	ds_read_b64_tr_b16 v[54:55], v26 offset:64
	ds_read_b64_tr_b16 v[58:59], v26 offset:96
	ds_read_b64_tr_b16 v[56:57], v26 offset:640
	ds_read_b64_tr_b16 v[60:61], v26 offset:672
	s_waitcnt lgkmcnt(6)
	v_mfma_f32_16x16x32_bf16 v[26:29], v[14:17], v[38:41], 0
	s_waitcnt lgkmcnt(4)
	v_mfma_f32_16x16x32_bf16 v[30:33], v[18:21], v[38:41], 0
	s_waitcnt lgkmcnt(1)
	v_mfma_f32_16x16x32_bf16 v[14:17], v[54:57], v[38:41], 0
	s_waitcnt lgkmcnt(0)
	v_mfma_f32_16x16x32_bf16 v[18:21], v[58:61], v[38:41], 0
	s_or_b64 exec, exec, s[16:17]
	v_cmp_lt_i32_e32 vcc, 0, v53
	s_and_saveexec_b64 s[16:17], vcc
	s_cbranch_execnz .LBB0_391

.LBB0_394:
	s_or_b64 exec, exec, s[16:17]
	v_and_b32_e32 v13, 64, v1
	v_xor_b32_e32 v12, 16, v1
	v_add_u32_e32 v13, 64, v13
	v_cmp_lt_i32_e32 vcc, v12, v13
	s_lshl_b32 s14, s18, 6
	v_lshlrev_b64 v[10:11], 11, v[48:49]
	v_cndmask_b32_e32 v12, v1, v12, vcc
	v_cmp_eq_u32_e32 vcc, 0, v50
	v_lshlrev_b32_e32 v34, 2, v12
	v_lshl_add_u64 v[10:11], s[4:5], 0, v[10:11]
	v_cndmask_b32_e32 v22, v27, v31, vcc
	v_cndmask_b32_e32 v23, v26, v30, vcc
	v_cndmask_b32_e32 v12, v29, v33, vcc
	v_cndmask_b32_e32 v13, v28, v32, vcc
	ds_bpermute_b32 v36, v34, v22
	ds_bpermute_b32 v37, v34, v23
	ds_bpermute_b32 v24, v34, v12
	ds_bpermute_b32 v35, v34, v13
	s_lshl_b32 s14, s14, 1
	s_waitcnt lgkmcnt(3)
	v_cndmask_b32_e32 v23, v36, v27, vcc
	s_waitcnt lgkmcnt(2)
	v_cndmask_b32_e32 v22, v37, v26, vcc
	s_waitcnt lgkmcnt(1)
	v_cndmask_b32_e32 v13, v24, v29, vcc
	s_waitcnt lgkmcnt(0)
	v_cndmask_b32_e32 v12, v35, v28, vcc
	s_cmp_lg_u64 s[44:45], 0
	s_cbranch_scc1 .Lg_w0_c
	s_waitcnt vmcnt(1)
	s_branch .Lg_j_c
.Lg_w0_c:
	s_waitcnt vmcnt(2)
.Lg_j_c:
	v_lshlrev_b32_e32 v28, 16, v6
	v_and_b32_e32 v29, 0xffff0000, v6
	v_pk_add_f32 v[22:23], v[46:47], v[22:23] op_sel_hi:[0,1]
	v_pk_mul_f32 v[22:23], v[22:23], v[28:29]
	v_pk_add_f32 v[12:13], v[46:47], v[12:13] op_sel_hi:[0,1]
	v_cvt_pk_bf16_f32 v6, v22, v23
	v_lshlrev_b32_e32 v22, 16, v7
	v_and_b32_e32 v23, 0xffff0000, v7
	v_cndmask_b32_e32 v27, v31, v36, vcc
	v_cndmask_b32_e32 v26, v30, v37, vcc
	v_pk_mul_f32 v[12:13], v[12:13], v[22:23]
	v_pk_add_f32 v[22:23], v[46:47], v[26:27] op_sel_hi:[0,1]
	v_cvt_pk_bf16_f32 v7, v12, v13
	v_lshlrev_b32_e32 v12, 16, v8
	v_and_b32_e32 v13, 0xffff0000, v8
	v_cndmask_b32_e32 v25, v33, v24, vcc
	v_cndmask_b32_e32 v24, v32, v35, vcc
	v_pk_mul_f32 v[12:13], v[22:23], v[12:13]
	v_pk_add_f32 v[22:23], v[46:47], v[24:25] op_sel_hi:[0,1]
	v_cvt_pk_bf16_f32 v8, v12, v13
	v_lshlrev_b32_e32 v12, 16, v9
	v_and_b32_e32 v13, 0xffff0000, v9
	v_pk_mul_f32 v[12:13], v[22:23], v[12:13]
	v_cndmask_b32_e32 v22, v15, v19, vcc
	v_cndmask_b32_e32 v23, v14, v18, vcc
	v_cvt_pk_bf16_f32 v9, v12, v13
	v_cndmask_b32_e32 v12, v17, v21, vcc
	v_cndmask_b32_e32 v13, v16, v20, vcc
	ds_bpermute_b32 v22, v34, v22
	ds_bpermute_b32 v23, v34, v23
	ds_bpermute_b32 v12, v34, v12
	ds_bpermute_b32 v24, v34, v13
	v_lshl_add_u64 v[10:11], v[10:11], 0, s[14:15]
	v_lshl_add_u64 v[10:11], v[10:11], 0, v[42:43]
	global_store_dwordx4 v[10:11], v[6:9], off
	s_waitcnt lgkmcnt(1)
	v_cndmask_b32_e32 v13, v21, v12, vcc
	v_cndmask_b32_e32 v9, v22, v15, vcc
	v_cndmask_b32_e32 v8, v23, v14, vcc
	v_cndmask_b32_e32 v7, v12, v17, vcc
	s_waitcnt lgkmcnt(0)
	v_cndmask_b32_e32 v6, v24, v16, vcc
	s_cmp_lg_u64 s[44:45], 0
	s_cbranch_scc1 .Lg_w0_d
	s_waitcnt vmcnt(1)
	s_branch .Lg_j_d

.Lg_j_d:
	v_lshlrev_b32_e32 v16, 16, v2
	v_and_b32_e32 v17, 0xffff0000, v2
	v_pk_add_f32 v[8:9], v[46:47], v[8:9] op_sel_hi:[0,1]
	v_pk_mul_f32 v[8:9], v[8:9], v[16:17]
	v_pk_add_f32 v[6:7], v[46:47], v[6:7] op_sel_hi:[0,1]
	v_cvt_pk_bf16_f32 v2, v8, v9
	v_lshlrev_b32_e32 v8, 16, v3
	v_and_b32_e32 v9, 0xffff0000, v3
	v_cndmask_b32_e32 v15, v19, v22, vcc
	v_cndmask_b32_e32 v14, v18, v23, vcc
	v_pk_mul_f32 v[6:7], v[6:7], v[8:9]
	v_pk_add_f32 v[8:9], v[46:47], v[14:15] op_sel_hi:[0,1]
	v_cvt_pk_bf16_f32 v3, v6, v7
	v_lshlrev_b32_e32 v6, 16, v4
	v_and_b32_e32 v7, 0xffff0000, v4
	v_cndmask_b32_e32 v12, v20, v24, vcc
	v_pk_mul_f32 v[6:7], v[8:9], v[6:7]
	v_pk_add_f32 v[8:9], v[46:47], v[12:13] op_sel_hi:[0,1]
	v_cvt_pk_bf16_f32 v4, v6, v7
	v_lshlrev_b32_e32 v6, 16, v5
	v_and_b32_e32 v7, 0xffff0000, v5
	v_pk_mul_f32 v[6:7], v[8:9], v[6:7]
	s_nop 0
	v_cvt_pk_bf16_f32 v5, v6, v7
	global_store_dwordx4 v[10:11], v[2:5], off offset:64
	s_barrier
	s_and_saveexec_b64 s[16:17], s[44:45]
	s_cbranch_execz .LBB0_381
	s_waitcnt vmcnt(0)
	ds_write_b32 v43, v67 offset:8
	s_branch .LBB0_381

.LBB0_450:
	s_or_b64 exec, exec, s[20:21]
	v_mov_b32_e32 v84, v0
	s_waitcnt lgkmcnt(0)
	s_barrier
	s_lshl_b64 s[18:19], s[18:19], 11
	v_and_b32_e32 v88, 15, v84
	v_bfe_u32 v85, v84, 4, 2
	v_lshlrev_b32_e32 v1, 4, v85
	v_mul_u32_u24_e32 v54, 0x90, v88
	v_add3_u32 v1, 16, v1, v54
	ds_read_b128 v[54:57], v1
	ds_read_b128 v[58:61], v1 offset:64
	s_waitcnt vmcnt(3) lgkmcnt(1)
	v_mfma_f32_16x16x32_bf16 v[62:65], v[54:57], v[50:53], v[2:5]
	ds_read_b128 v[66:69], v1 offset:2304
	ds_read_b128 v[70:73], v1 offset:2368
	s_add_u32 s18, s14, s18
	s_addc_u32 s19, s15, s19
	s_waitcnt vmcnt(1)
	v_mfma_f32_16x16x32_bf16 v[54:57], v[54:57], v[42:45], v[2:5]
	s_add_u32 s18, s18, s31
	s_addc_u32 s19, s19, 0
	s_add_u32 s20, s22, s31
	s_waitcnt lgkmcnt(1)
	v_mfma_f32_16x16x32_bf16 v[74:77], v[66:69], v[50:53], v[2:5]
	s_addc_u32 s21, s23, 0
	v_lshlrev_b32_e32 v166, 3, v85
	s_add_i32 s30, s30, s33
	v_mfma_f32_16x16x32_bf16 v[62:65], v[58:61], v[46:49], v[62:65]
	s_add_i32 s3, s3, s24
	s_add_i32 s25, s25, s26
	s_cmpk_lt_i32 s30, 0x100
	s_waitcnt vmcnt(0)
	v_mfma_f32_16x16x32_bf16 v[54:57], v[58:61], v[38:41], v[54:57]
	v_bfe_u32 v58, v84, 2, 2
	v_lshl_or_b32 v78, v85, 2, v58
	s_nop 0
	v_exp_f32_e32 v79, v62
	v_mfma_f32_16x16x32_bf16 v[58:61], v[66:69], v[42:45], v[2:5]
	v_exp_f32_e32 v66, v63
	v_exp_f32_e32 v67, v64
	v_exp_f32_e32 v68, v65
	s_waitcnt lgkmcnt(0)
	v_mfma_f32_16x16x32_bf16 v[62:65], v[70:73], v[46:49], v[74:77]
	v_exp_f32_e32 v82, v56
	v_exp_f32_e32 v83, v57
	v_mfma_f32_16x16x32_bf16 v[58:61], v[70:73], v[38:41], v[58:61]
	s_nop 4
	v_exp_f32_e32 v69, v62
	v_exp_f32_e32 v74, v63
	v_exp_f32_e32 v75, v64
	v_exp_f32_e32 v65, v65
	v_cvt_pk_bf16_f32 v62, v79, v66
	v_cvt_pk_bf16_f32 v63, v67, v68
	v_exp_f32_e32 v66, v54
	v_exp_f32_e32 v67, v55
	v_lshlrev_b32_e32 v55, 3, v84
	v_mul_u32_u24_e32 v54, 0x90, v78
	v_and_b32_e32 v55, 24, v55
	v_add3_u32 v168, 16, v54, v55
	v_cvt_pk_bf16_f32 v64, v69, v74
	v_cvt_pk_bf16_f32 v65, v75, v65
	v_exp_f32_e32 v86, v58
	ds_read_b64_tr_b16 v[56:57], v168 offset:39168
	ds_read_b64_tr_b16 v[54:55], v168 offset:36864
	v_cvt_pk_bf16_f32 v58, v66, v67
	ds_read_b64_tr_b16 v[66:67], v168 offset:36896
	ds_read_b64_tr_b16 v[70:71], v168 offset:36928
	ds_read_b64_tr_b16 v[74:75], v168 offset:36960
	ds_read_b64_tr_b16 v[68:69], v168 offset:39200
	ds_read_b64_tr_b16 v[72:73], v168 offset:39232
	ds_read_b64_tr_b16 v[76:77], v168 offset:39264
	ds_read_b128 v[106:109], v1 offset:4608
	ds_read_b128 v[110:113], v1 offset:4672
	v_exp_f32_e32 v87, v59
	v_exp_f32_e32 v89, v60
	v_exp_f32_e32 v61, v61
	ds_read_b128 v[114:117], v1 offset:6912
	ds_read_b128 v[122:125], v1 offset:6976
	v_cvt_pk_bf16_f32 v59, v82, v83
	v_cvt_pk_bf16_f32 v60, v86, v87
	v_cvt_pk_bf16_f32 v61, v89, v61
	s_waitcnt lgkmcnt(10)
	v_mfma_f32_16x16x32_bf16 v[78:81], v[54:57], v[62:65], 0
	v_ashrrev_i32_e32 v84, 1, v84
	v_and_or_b32 v194, v84, s28, v88
	v_lshl_add_u64 v[84:85], s[20:21], 0, v[166:167]
	v_mfma_f32_16x16x32_bf16 v[90:93], v[54:57], v[58:61], 0
	v_lshl_add_u64 v[228:229], v[84:85], 0, s[16:17]
	v_mad_i64_i32 v[230:231], s[20:21], v194, s27, v[228:229]
	s_waitcnt lgkmcnt(3)
	v_mfma_f32_16x16x32_bf16 v[54:57], v[106:109], v[50:53], v[2:5]
	v_add_u32_e32 v195, 0x9000, v168
	s_waitcnt lgkmcnt(2)
	v_mfma_f32_16x16x32_bf16 v[118:121], v[110:113], v[46:49], v[54:57]
	s_waitcnt lgkmcnt(1)
	v_mfma_f32_16x16x32_bf16 v[126:129], v[114:117], v[50:53], v[2:5]
	s_nop 2
	v_mov_b64_e32 v[56:57], s[10:11]
	s_nop 1
	v_exp_f32_e32 v82, v118
	v_exp_f32_e32 v83, v119
	v_mfma_f32_16x16x32_bf16 v[106:109], v[106:109], v[42:45], v[2:5]
	v_exp_f32_e32 v86, v120
	v_exp_f32_e32 v87, v121
	v_mov_b64_e32 v[54:55], s[8:9]
	s_waitcnt lgkmcnt(0)
	v_mfma_f32_16x16x32_bf16 v[126:129], v[122:125], v[46:49], v[126:129]
	v_mfma_f32_16x16x32_bf16 v[106:109], v[110:113], v[38:41], v[106:109]
	v_cvt_pk_bf16_f32 v110, v82, v83
	s_nop 5
	v_exp_f32_e32 v89, v126
	v_exp_f32_e32 v118, v127
	v_mfma_f32_16x16x32_bf16 v[114:117], v[114:117], v[42:45], v[2:5]
	v_cvt_pk_bf16_f32 v111, v86, v87
	v_exp_f32_e32 v82, v106
	v_exp_f32_e32 v83, v107
	v_mfma_f32_16x16x32_bf16 v[114:117], v[122:125], v[38:41], v[114:117]
	v_exp_f32_e32 v86, v108
	v_exp_f32_e32 v87, v109
	ds_read_b64_tr_b16 v[106:107], v168 offset:41472
	ds_read_b64_tr_b16 v[108:109], v168 offset:43776
	v_exp_f32_e32 v119, v128
	v_exp_f32_e32 v120, v129
	v_cvt_pk_bf16_f32 v112, v89, v118
	s_nop 0
	v_exp_f32_e32 v89, v114
	v_exp_f32_e32 v130, v115
	v_exp_f32_e32 v131, v116
	v_exp_f32_e32 v117, v117
	v_cvt_pk_bf16_f32 v113, v119, v120
	v_cvt_pk_bf16_f32 v114, v82, v83
	v_cvt_pk_bf16_f32 v115, v86, v87
	v_cvt_pk_bf16_f32 v116, v89, v130
	v_cvt_pk_bf16_f32 v117, v131, v117
	v_mfma_f32_16x16x32_bf16 v[94:97], v[66:69], v[62:65], 0
	ds_read_b64_tr_b16 v[118:119], v168 offset:41504
	ds_read_b64_tr_b16 v[122:123], v168 offset:41536
	ds_read_b64_tr_b16 v[126:127], v168 offset:41568
	ds_read_b64_tr_b16 v[120:121], v168 offset:43808
	ds_read_b64_tr_b16 v[124:125], v168 offset:43840
	ds_read_b64_tr_b16 v[128:129], v168 offset:43872
	ds_read_b128 v[130:133], v1 offset:11520
	ds_read_b128 v[134:137], v1 offset:11584
	v_mfma_f32_16x16x32_bf16 v[66:69], v[66:69], v[58:61], 0
	s_waitcnt lgkmcnt(8)
	v_mfma_f32_16x16x32_bf16 v[78:81], v[106:109], v[110:113], v[78:81]
	v_mfma_f32_16x16x32_bf16 v[90:93], v[106:109], v[114:117], v[90:93]
	ds_read_b128 v[106:109], v1 offset:9216
	s_waitcnt lgkmcnt(5)
	v_mfma_f32_16x16x32_bf16 v[94:97], v[118:121], v[110:113], v[94:97]
	v_mfma_f32_16x16x32_bf16 v[66:69], v[118:121], v[114:117], v[66:69]
	ds_read_b128 v[118:121], v1 offset:9280
	v_mfma_f32_16x16x32_bf16 v[98:101], v[70:73], v[62:65], 0
	v_mfma_f32_16x16x32_bf16 v[70:73], v[70:73], v[58:61], 0
	s_waitcnt lgkmcnt(5)
	v_mfma_f32_16x16x32_bf16 v[98:101], v[122:125], v[110:113], v[98:101]
	v_mfma_f32_16x16x32_bf16 v[70:73], v[122:125], v[114:117], v[70:73]
	s_waitcnt lgkmcnt(1)
	v_mfma_f32_16x16x32_bf16 v[122:125], v[106:109], v[50:53], v[2:5]
	v_mfma_f32_16x16x32_bf16 v[138:141], v[130:133], v[50:53], v[2:5]
	s_waitcnt lgkmcnt(0)
	v_mfma_f32_16x16x32_bf16 v[122:125], v[118:121], v[46:49], v[122:125]
	v_mfma_f32_16x16x32_bf16 v[138:141], v[134:137], v[46:49], v[138:141]
	v_mfma_f32_16x16x32_bf16 v[106:109], v[106:109], v[42:45], v[2:5]
	s_nop 5
	v_exp_f32_e32 v82, v122
	v_exp_f32_e32 v89, v138
	v_exp_f32_e32 v122, v139
	v_exp_f32_e32 v83, v123
	v_exp_f32_e32 v86, v124
	v_exp_f32_e32 v87, v125
	v_mfma_f32_16x16x32_bf16 v[106:109], v[118:121], v[38:41], v[106:109]
	v_cvt_pk_bf16_f32 v120, v89, v122
	v_exp_f32_e32 v138, v140
	v_exp_f32_e32 v139, v141
	v_mfma_f32_16x16x32_bf16 v[122:125], v[130:133], v[42:45], v[2:5]
	v_cvt_pk_bf16_f32 v118, v82, v83
	v_cvt_pk_bf16_f32 v119, v86, v87
	s_nop 1
	v_exp_f32_e32 v82, v106
	v_mfma_f32_16x16x32_bf16 v[122:125], v[134:137], v[38:41], v[122:125]
	v_exp_f32_e32 v83, v107
	v_exp_f32_e32 v86, v108
	v_exp_f32_e32 v87, v109
	v_mfma_f32_16x16x32_bf16 v[102:105], v[74:77], v[62:65], 0
	v_cvt_pk_bf16_f32 v121, v138, v139
	s_nop 2
	v_exp_f32_e32 v89, v122
	v_exp_f32_e32 v108, v123
	v_mfma_f32_16x16x32_bf16 v[74:77], v[74:77], v[58:61], 0
	v_exp_f32_e32 v109, v124
	v_exp_f32_e32 v134, v125
	ds_read_b64_tr_b16 v[122:123], v168 offset:46080
	ds_read_b64_tr_b16 v[124:125], v168 offset:48384
	v_mfma_f32_16x16x32_bf16 v[62:65], v[54:57], v[62:65], 0
	v_cvt_pk_bf16_f32 v106, v82, v83
	v_cvt_pk_bf16_f32 v107, v86, v87
	v_cvt_pk_bf16_f32 v108, v89, v108
	v_mfma_f32_16x16x32_bf16 v[102:105], v[126:129], v[110:113], v[102:105]
	v_cvt_pk_bf16_f32 v109, v109, v134
	v_mfma_f32_16x16x32_bf16 v[74:77], v[126:129], v[114:117], v[74:77]
	v_mfma_f32_16x16x32_bf16 v[62:65], v[54:57], v[110:113], v[62:65]
	ds_read_b64_tr_b16 v[110:111], v168 offset:46112
	ds_read_b64_tr_b16 v[126:127], v168 offset:46144
	ds_read_b64_tr_b16 v[130:131], v168 offset:46176
	ds_read_b64_tr_b16 v[112:113], v168 offset:48416
	ds_read_b64_tr_b16 v[128:129], v168 offset:48448
	ds_read_b64_tr_b16 v[132:133], v168 offset:48480
	s_waitcnt lgkmcnt(6)
	v_mfma_f32_16x16x32_bf16 v[78:81], v[122:125], v[118:121], v[78:81]
	v_mfma_f32_16x16x32_bf16 v[90:93], v[122:125], v[106:109], v[90:93]
	ds_read_b128 v[122:125], v1 offset:16128
	s_waitcnt lgkmcnt(2)
	v_mfma_f32_16x16x32_bf16 v[138:141], v[126:129], v[118:121], v[98:101]
	s_nop 2
	ds_read_b128 v[98:101], v1 offset:13824
	v_mfma_f32_16x16x32_bf16 v[94:97], v[110:113], v[118:121], v[94:97]
	v_mfma_f32_16x16x32_bf16 v[66:69], v[110:113], v[106:109], v[66:69]
	ds_read_b128 v[110:113], v1 offset:13888
	v_mfma_f32_16x16x32_bf16 v[70:73], v[126:129], v[106:109], v[70:73]
	ds_read_b128 v[126:129], v1 offset:16192
	v_mfma_f32_16x16x32_bf16 v[58:61], v[54:57], v[58:61], 0
	v_mfma_f32_16x16x32_bf16 v[58:61], v[54:57], v[114:117], v[58:61]
	s_waitcnt lgkmcnt(2)
	v_mfma_f32_16x16x32_bf16 v[114:117], v[98:101], v[50:53], v[2:5]
	v_mfma_f32_16x16x32_bf16 v[134:137], v[122:125], v[50:53], v[2:5]
	v_mfma_f32_16x16x32_bf16 v[98:101], v[98:101], v[42:45], v[2:5]
	s_waitcnt lgkmcnt(1)
	v_mfma_f32_16x16x32_bf16 v[114:117], v[110:113], v[46:49], v[114:117]
	s_waitcnt lgkmcnt(0)
	v_mfma_f32_16x16x32_bf16 v[134:137], v[126:129], v[46:49], v[134:137]
	v_mfma_f32_16x16x32_bf16 v[98:101], v[110:113], v[38:41], v[98:101]
	s_nop 4
	v_exp_f32_e32 v82, v114
	v_exp_f32_e32 v83, v115
	v_exp_f32_e32 v86, v116
	v_mfma_f32_16x16x32_bf16 v[110:113], v[122:125], v[42:45], v[2:5]
	v_exp_f32_e32 v87, v117
	v_exp_f32_e32 v89, v134
	v_exp_f32_e32 v114, v135
	v_mfma_f32_16x16x32_bf16 v[110:113], v[126:129], v[38:41], v[110:113]
	v_cvt_pk_bf16_f32 v142, v82, v83
	v_cvt_pk_bf16_f32 v143, v86, v87
	v_cvt_pk_bf16_f32 v144, v89, v114
	v_exp_f32_e32 v82, v98
	v_exp_f32_e32 v83, v99
	v_exp_f32_e32 v86, v100
	v_exp_f32_e32 v87, v101
	s_nop 0
	v_exp_f32_e32 v89, v110
	v_exp_f32_e32 v98, v111
	v_exp_f32_e32 v99, v112
	v_exp_f32_e32 v100, v113
	v_mfma_f32_16x16x32_bf16 v[150:153], v[130:133], v[106:109], v[74:77]
	s_nop 2
	ds_read_b64_tr_b16 v[74:75], v168 offset:50688
	ds_read_b64_tr_b16 v[76:77], v168 offset:52992
	v_exp_f32_e32 v115, v136
	v_exp_f32_e32 v116, v137
	v_cvt_pk_bf16_f32 v154, v82, v83
	v_cvt_pk_bf16_f32 v155, v86, v87
	v_cvt_pk_bf16_f32 v156, v89, v98
	v_cvt_pk_bf16_f32 v157, v99, v100
	v_mfma_f32_16x16x32_bf16 v[126:129], v[130:133], v[118:121], v[102:105]
	v_cvt_pk_bf16_f32 v145, v115, v116
	v_mfma_f32_16x16x32_bf16 v[170:173], v[54:57], v[118:121], v[62:65]
	s_nop 2
	ds_read_b64_tr_b16 v[62:63], v168 offset:50720
	ds_read_b64_tr_b16 v[102:103], v168 offset:50752
	ds_read_b64_tr_b16 v[174:175], v168 offset:50784
	ds_read_b64_tr_b16 v[64:65], v168 offset:53024
	ds_read_b64_tr_b16 v[104:105], v168 offset:53056
	ds_read_b64_tr_b16 v[176:177], v168 offset:53088
	v_mfma_f32_16x16x32_bf16 v[178:181], v[54:57], v[106:109], v[58:61]
	s_waitcnt lgkmcnt(6)
	v_mfma_f32_16x16x32_bf16 v[110:113], v[74:77], v[154:157], v[90:93]
	s_nop 0
	ds_read_b128 v[58:61], v1 offset:18432
	s_nop 0
	ds_read_b128 v[90:93], v1 offset:20736
	v_mfma_f32_16x16x32_bf16 v[134:137], v[74:77], v[142:145], v[78:81]
	ds_read_b128 v[74:77], v1 offset:18496
	s_waitcnt lgkmcnt(5)
	v_mfma_f32_16x16x32_bf16 v[122:125], v[62:65], v[142:145], v[94:97]
	s_nop 2
	ds_read_b128 v[94:97], v1 offset:20800
	s_waitcnt lgkmcnt(3)
	v_mfma_f32_16x16x32_bf16 v[78:81], v[58:61], v[50:53], v[2:5]
	s_waitcnt lgkmcnt(2)
	v_mfma_f32_16x16x32_bf16 v[98:101], v[90:93], v[50:53], v[2:5]
	v_mfma_f32_16x16x32_bf16 v[58:61], v[58:61], v[42:45], v[2:5]
	s_waitcnt lgkmcnt(1)
	v_mfma_f32_16x16x32_bf16 v[78:81], v[74:77], v[46:49], v[78:81]
	s_waitcnt lgkmcnt(0)
	v_mfma_f32_16x16x32_bf16 v[98:101], v[94:97], v[46:49], v[98:101]
	v_mfma_f32_16x16x32_bf16 v[58:61], v[74:77], v[38:41], v[58:61]
	s_nop 4
	v_exp_f32_e32 v78, v78
	s_nop 0
	v_exp_f32_e32 v82, v98
	v_exp_f32_e32 v83, v99
	v_mfma_f32_16x16x32_bf16 v[74:77], v[90:93], v[42:45], v[2:5]
	v_exp_f32_e32 v86, v100
	v_exp_f32_e32 v87, v101
	ds_read_b128 v[98:101], v1 offset:23040
	v_mfma_f32_16x16x32_bf16 v[74:77], v[94:97], v[38:41], v[74:77]
	ds_read_b128 v[94:97], v1 offset:25344
	v_exp_f32_e32 v58, v58
	v_exp_f32_e32 v59, v59
	v_exp_f32_e32 v60, v60
	v_exp_f32_e32 v61, v61
	s_nop 2
	v_exp_f32_e32 v74, v74
	v_exp_f32_e32 v75, v75
	v_mfma_f32_16x16x32_bf16 v[114:117], v[62:65], v[154:157], v[66:69]
	v_exp_f32_e32 v62, v76
	v_exp_f32_e32 v63, v77
	v_cvt_pk_bf16_f32 v58, v58, v59
	v_mfma_f32_16x16x32_bf16 v[130:133], v[102:105], v[142:145], v[138:141]
	v_cvt_pk_bf16_f32 v59, v60, v61
	v_cvt_pk_bf16_f32 v60, v74, v75
	v_cvt_pk_bf16_f32 v61, v62, v63
	v_mfma_f32_16x16x32_bf16 v[66:69], v[102:105], v[154:157], v[70:73]
	ds_read_b128 v[102:105], v1 offset:23104
	ds_read_b64_tr_b16 v[162:163], v168 offset:55296
	ds_read_b64_tr_b16 v[158:159], v168 offset:55328
	ds_read_b64_tr_b16 v[74:75], v168 offset:55360
	ds_read_b64_tr_b16 v[62:63], v168 offset:55392
	ds_read_b128 v[106:109], v1 offset:25408
	v_exp_f32_e32 v79, v79
	s_waitcnt lgkmcnt(7)
	v_mfma_f32_16x16x32_bf16 v[70:73], v[98:101], v[50:53], v[2:5]
	v_exp_f32_e32 v80, v80
	v_exp_f32_e32 v81, v81
	v_cvt_pk_bf16_f32 v78, v78, v79
	s_waitcnt lgkmcnt(6)
	v_mfma_f32_16x16x32_bf16 v[90:93], v[94:97], v[50:53], v[2:5]
	ds_read_b64_tr_b16 v[164:165], v168 offset:57600
	ds_read_b64_tr_b16 v[160:161], v168 offset:57632
	ds_read_b64_tr_b16 v[76:77], v168 offset:57664
	ds_read_b64_tr_b16 v[64:65], v168 offset:57696
	v_cvt_pk_bf16_f32 v79, v80, v81
	v_cvt_pk_bf16_f32 v80, v82, v83
	s_waitcnt lgkmcnt(9)
	v_mfma_f32_16x16x32_bf16 v[70:73], v[102:105], v[46:49], v[70:73]
	v_cvt_pk_bf16_f32 v81, v86, v87
	s_waitcnt lgkmcnt(4)
	v_mfma_f32_16x16x32_bf16 v[90:93], v[106:109], v[46:49], v[90:93]
	v_mfma_f32_16x16x32_bf16 v[146:149], v[174:177], v[142:145], v[126:129]
	s_nop 3
	v_exp_f32_e32 v70, v70
	v_exp_f32_e32 v71, v71
	v_exp_f32_e32 v82, v72
	v_exp_f32_e32 v83, v73
	v_exp_f32_e32 v86, v90
	v_exp_f32_e32 v87, v91
	v_exp_f32_e32 v89, v92
	v_exp_f32_e32 v90, v93
	v_cvt_pk_bf16_f32 v118, v70, v71
	v_mfma_f32_16x16x32_bf16 v[70:73], v[174:177], v[154:157], v[150:153]
	v_cvt_pk_bf16_f32 v119, v82, v83
	v_cvt_pk_bf16_f32 v120, v86, v87
	v_cvt_pk_bf16_f32 v121, v89, v90
	ds_read_b64_tr_b16 v[126:127], v168 offset:59904
	ds_read_b64_tr_b16 v[90:91], v168 offset:59936
	ds_read_b64_tr_b16 v[82:83], v168 offset:59968
	ds_read_b64_tr_b16 v[86:87], v168 offset:60000
	ds_read_b128 v[150:153], v1 offset:27648
	ds_read_b128 v[138:141], v1 offset:27712
	global_load_dwordx2 v[232:233], v[230:231], off
	global_load_dwordx2 v[6:7], v[230:231], off offset:32
	global_load_dwordx2 v[8:9], v[230:231], off offset:64
	global_load_dwordx2 v[10:11], v[230:231], off offset:96
	s_mov_b32 s74, 0x1a000
	s_mov_b32 s75, 0
	v_lshl_add_u64 v[12:13], v[230:231], 0, s[74:75]
	global_load_dwordx2 v[14:15], v[12:13], off
	global_load_dwordx2 v[16:17], v[12:13], off offset:32
	global_load_dwordx2 v[18:19], v[12:13], off offset:64
	global_load_dwordx2 v[20:21], v[12:13], off offset:96
	v_mfma_f32_16x16x32_bf16 v[170:173], v[54:57], v[142:145], v[170:173]
	ds_read_b128 v[142:145], v1 offset:29952
	v_mfma_f32_16x16x32_bf16 v[154:157], v[54:57], v[154:157], v[178:181]
	s_nop 2
	ds_read_b128 v[178:181], v1 offset:30016
	s_waitcnt lgkmcnt(3)
	v_mfma_f32_16x16x32_bf16 v[174:177], v[150:153], v[50:53], v[2:5]
	ds_read_b64_tr_b16 v[128:129], v168 offset:62208
	ds_read_b64_tr_b16 v[92:93], v168 offset:62240
	ds_read_b64_tr_b16 v[84:85], v168 offset:62272
	ds_read_b64_tr_b16 v[88:89], v168 offset:62304
	s_waitcnt lgkmcnt(5)
	v_mfma_f32_16x16x32_bf16 v[182:185], v[142:145], v[50:53], v[2:5]
	v_mfma_f32_16x16x32_bf16 v[174:177], v[138:141], v[46:49], v[174:177]
	s_waitcnt lgkmcnt(4)
	v_mfma_f32_16x16x32_bf16 v[182:185], v[178:181], v[46:49], v[182:185]
	v_mfma_f32_16x16x32_bf16 v[134:137], v[162:165], v[78:81], v[134:137]
	s_nop 4
	v_exp_f32_e32 v169, v174
	v_exp_f32_e32 v186, v175
	v_exp_f32_e32 v187, v176
	v_exp_f32_e32 v188, v177
	v_exp_f32_e32 v189, v182
	v_exp_f32_e32 v190, v183
	ds_read_b128 v[174:177], v1 offset:32256
	v_mfma_f32_16x16x32_bf16 v[162:165], v[162:165], v[58:61], v[110:113]
	v_cvt_pk_bf16_f32 v182, v169, v186
	v_cvt_pk_bf16_f32 v183, v187, v188
	s_nop 0
	v_exp_f32_e32 v110, v184
	v_cvt_pk_bf16_f32 v184, v189, v190
	ds_read_b128 v[186:189], v1 offset:32320
	ds_read_b128 v[190:193], v1 offset:34560
	s_waitcnt lgkmcnt(2)
	v_mfma_f32_16x16x32_bf16 v[200:203], v[174:177], v[50:53], v[2:5]
	v_exp_f32_e32 v111, v185
	s_nop 0
	v_cvt_pk_bf16_f32 v185, v110, v111
	s_waitcnt lgkmcnt(1)
	v_mfma_f32_16x16x32_bf16 v[200:203], v[186:189], v[46:49], v[200:203]
	ds_read_b64_tr_b16 v[204:205], v168 offset:64512
	ds_read_b64_tr_b16 v[208:209], v168 offset:64544
	ds_read_b64_tr_b16 v[212:213], v168 offset:64576
	ds_read_b64_tr_b16 v[110:111], v168 offset:64608
	ds_read_b128 v[216:219], v1 offset:34624
	ds_read_b64_tr_b16 v[206:207], v195 offset:29952
	ds_read_b64_tr_b16 v[210:211], v195 offset:29984
	ds_read_b64_tr_b16 v[214:215], v195 offset:30016
	ds_read_b64_tr_b16 v[112:113], v195 offset:30048
	v_exp_f32_e32 v1, v200
	s_waitcnt lgkmcnt(9)
	v_mfma_f32_16x16x32_bf16 v[50:53], v[190:193], v[50:53], v[2:5]
	v_exp_f32_e32 v168, v201
	v_exp_f32_e32 v196, v202
	v_exp_f32_e32 v198, v203
	v_mfma_f32_16x16x32_bf16 v[170:173], v[54:57], v[78:81], v[170:173]
	s_waitcnt lgkmcnt(4)
	v_mfma_f32_16x16x32_bf16 v[46:49], v[216:219], v[46:49], v[50:53]
	v_mfma_f32_16x16x32_bf16 v[50:53], v[126:129], v[118:121], v[134:137]
	s_nop 2
	v_cvt_pk_bf16_f32 v134, v1, v168
	v_mfma_f32_16x16x32_bf16 v[168:171], v[54:57], v[118:121], v[170:173]
	s_nop 1
	v_exp_f32_e32 v46, v46
	v_exp_f32_e32 v47, v47
	v_exp_f32_e32 v48, v48
	v_exp_f32_e32 v49, v49
	v_mfma_f32_16x16x32_bf16 v[168:171], v[54:57], v[182:185], v[168:171]
	v_cvt_pk_bf16_f32 v135, v196, v198
	v_cvt_pk_bf16_f32 v136, v46, v47
	v_cvt_pk_bf16_f32 v137, v48, v49
	s_waitcnt lgkmcnt(3)
	v_mfma_f32_16x16x32_bf16 v[50:53], v[204:207], v[182:185], v[50:53]
	ds_read_b64_tr_b16 v[200:201], v195 offset:32256
	ds_read_b64_tr_b16 v[220:221], v195 offset:32288
	ds_read_b64_tr_b16 v[224:225], v195 offset:32320
	ds_read_b64_tr_b16 v[46:47], v195 offset:32352
	ds_read_b64_tr_b16 v[202:203], v195 offset:34560
	ds_read_b64_tr_b16 v[222:223], v195 offset:34592
	ds_read_b64_tr_b16 v[226:227], v195 offset:34624
	ds_read_b64_tr_b16 v[48:49], v195 offset:34656
	v_lshl_add_u64 v[172:173], s[18:19], 0, v[166:167]
	v_mfma_f32_16x16x32_bf16 v[168:171], v[54:57], v[134:137], v[168:171]
	v_ashrrev_i32_e32 v195, 31, v194
	v_mfma_f32_16x16x32_bf16 v[122:125], v[158:161], v[78:81], v[122:125]
	s_waitcnt lgkmcnt(3)
	v_mfma_f32_16x16x32_bf16 v[50:53], v[200:203], v[134:137], v[50:53]
	s_nop 3
	v_rcp_f32_e32 v166, v168
	s_waitcnt vmcnt(7)
	v_lshlrev_b32_e32 v170, 16, v232
	v_and_b32_e32 v171, 0xffff0000, v232
	v_mfma_f32_16x16x32_bf16 v[122:125], v[90:93], v[118:121], v[122:125]
	v_lshlrev_b64 v[168:169], 11, v[194:195]
	v_pk_mul_f32 v[50:51], v[50:51], v[166:167] op_sel_hi:[1,0]
	v_lshl_add_u64 v[168:169], v[172:173], 0, v[168:169]
	v_mfma_f32_16x16x32_bf16 v[114:117], v[158:161], v[58:61], v[114:117]
	v_mul_f32_e64 v50, v50, v170
	v_mul_f32_e64 v51, v51, v171
	v_pk_mul_f32 v[160:161], v[52:53], v[166:167] op_sel_hi:[1,0]
	v_lshlrev_b32_e32 v170, 16, v233
	v_and_b32_e32 v171, 0xffff0000, v233
	v_cvt_pk_bf16_f32 v158, v50, v51
	v_mfma_f32_16x16x32_bf16 v[50:53], v[208:211], v[182:185], v[122:125]
	s_nop 2
	v_mul_f32_e64 v122, v160, v170
	v_mul_f32_e64 v123, v161, v171
	s_waitcnt lgkmcnt(2)
	v_mfma_f32_16x16x32_bf16 v[50:53], v[220:223], v[134:137], v[50:53]
	v_cvt_pk_bf16_f32 v159, v122, v123
	global_store_dwordx2 v[168:169], v[158:159], off offset:1536
	v_mfma_f32_16x16x32_bf16 v[122:125], v[74:77], v[78:81], v[130:133]
	s_waitcnt vmcnt(7)
	v_lshlrev_b32_e32 v160, 16, v6
	v_mfma_f32_16x16x32_bf16 v[122:125], v[82:85], v[118:121], v[122:125]
	s_nop 0
	v_mul_f32_e64 v50, v50, v166
	v_mul_f32_e64 v51, v51, v166
	v_and_b32_e32 v161, 0xffff0000, v6
	v_pk_mul_f32 v[50:51], v[50:51], v[160:161]
	v_pk_mul_f32 v[132:133], v[52:53], v[166:167] op_sel_hi:[1,0]
	v_lshlrev_b32_e32 v158, 16, v7
	v_and_b32_e32 v159, 0xffff0000, v7
	v_cvt_pk_bf16_f32 v130, v50, v51
	v_mfma_f32_16x16x32_bf16 v[50:53], v[212:215], v[182:185], v[122:125]
	s_nop 2
	v_mul_f32_e64 v122, v132, v158
	v_mul_f32_e64 v123, v133, v159
	s_waitcnt lgkmcnt(1)
	v_mfma_f32_16x16x32_bf16 v[50:53], v[224:227], v[134:137], v[50:53]
	v_cvt_pk_bf16_f32 v131, v122, v123
	global_store_dwordx2 v[168:169], v[130:131], off offset:1568
	v_mfma_f32_16x16x32_bf16 v[98:101], v[98:101], v[42:45], v[2:5]
	s_waitcnt vmcnt(7)
	v_lshlrev_b32_e32 v124, 16, v8
	s_nop 1
	v_pk_mul_f32 v[50:51], v[50:51], v[166:167] op_sel_hi:[1,0]
	v_and_b32_e32 v125, 0xffff0000, v8
	v_pk_mul_f32 v[50:51], v[50:51], v[124:125]
	v_pk_mul_f32 v[124:125], v[52:53], v[166:167] op_sel_hi:[1,0]
	v_lshlrev_b32_e32 v130, 16, v9
	v_and_b32_e32 v131, 0xffff0000, v9
	v_cvt_pk_bf16_f32 v122, v50, v51
	v_mfma_f32_16x16x32_bf16 v[50:53], v[102:105], v[38:41], v[98:101]
	s_nop 2
	v_mul_f32_e64 v98, v124, v130
	v_mul_f32_e64 v99, v125, v131
	v_mfma_f32_16x16x32_bf16 v[78:81], v[62:65], v[78:81], v[146:149]
	v_cvt_pk_bf16_f32 v123, v98, v99
	global_store_dwordx2 v[168:169], v[122:123], off offset:1600
	v_mfma_f32_16x16x32_bf16 v[94:97], v[94:97], v[42:45], v[2:5]
	v_exp_f32_e32 v1, v50
	v_exp_f32_e32 v98, v51
	v_exp_f32_e32 v99, v52
	v_exp_f32_e32 v100, v53
	v_mfma_f32_16x16x32_bf16 v[50:53], v[86:89], v[118:121], v[78:81]
	v_mfma_f32_16x16x32_bf16 v[94:97], v[106:109], v[38:41], v[94:97]
	s_nop 1
	v_cvt_pk_bf16_f32 v78, v1, v98
	v_cvt_pk_bf16_f32 v79, v99, v100
	s_waitcnt vmcnt(7)
	v_lshlrev_b32_e32 v98, 16, v10
	v_mfma_f32_16x16x32_bf16 v[50:53], v[110:113], v[182:185], v[50:53]
	s_nop 0
	v_exp_f32_e32 v94, v94
	v_exp_f32_e32 v80, v95
	v_exp_f32_e32 v81, v96
	v_exp_f32_e32 v95, v97
	s_waitcnt lgkmcnt(0)
	v_mfma_f32_16x16x32_bf16 v[50:53], v[46:49], v[134:137], v[50:53]
	v_cvt_pk_bf16_f32 v80, v94, v80
	v_and_b32_e32 v99, 0xffff0000, v10
	v_cvt_pk_bf16_f32 v81, v81, v95
	v_mfma_f32_16x16x32_bf16 v[94:97], v[54:57], v[58:61], v[154:157]
	v_lshlrev_b32_e32 v106, 16, v11
	s_nop 2
	v_pk_mul_f32 v[50:51], v[50:51], v[166:167] op_sel_hi:[1,0]
	v_pk_mul_f32 v[104:105], v[52:53], v[166:167] op_sel_hi:[1,0]
	v_pk_mul_f32 v[50:51], v[50:51], v[98:99]
	v_and_b32_e32 v107, 0xffff0000, v11
	v_cvt_pk_bf16_f32 v102, v50, v51
	v_mfma_f32_16x16x32_bf16 v[50:53], v[54:57], v[78:81], v[94:97]
	s_nop 2
	v_mul_f32_e64 v94, v104, v106
	v_mul_f32_e64 v95, v105, v107
	v_or_b32_e32 v106, 16, v194
	v_cvt_pk_bf16_f32 v103, v94, v95
	global_store_dwordx2 v[168:169], v[102:103], off offset:1632
	v_mad_i64_i32 v[108:109], s[18:19], v106, s27, v[228:229]
	v_mfma_f32_16x16x32_bf16 v[94:97], v[150:153], v[42:45], v[2:5]
	v_mfma_f32_16x16x32_bf16 v[102:105], v[142:145], v[42:45], v[2:5]
	v_mfma_f32_16x16x32_bf16 v[94:97], v[138:141], v[38:41], v[94:97]
	v_mfma_f32_16x16x32_bf16 v[102:105], v[178:181], v[38:41], v[102:105]
	v_mfma_f32_16x16x32_bf16 v[98:101], v[126:129], v[78:81], v[162:165]
	s_nop 5
	v_exp_f32_e32 v1, v94
	v_exp_f32_e32 v107, v95
	v_exp_f32_e32 v120, v96
	v_exp_f32_e32 v121, v97
	v_mfma_f32_16x16x32_bf16 v[94:97], v[174:177], v[42:45], v[2:5]
	v_exp_f32_e32 v122, v102
	v_exp_f32_e32 v123, v103
	v_exp_f32_e32 v124, v104
	v_mfma_f32_16x16x32_bf16 v[42:45], v[190:193], v[42:45], v[2:5]
	v_exp_f32_e32 v105, v105
	v_cvt_pk_bf16_f32 v102, v1, v107
	v_cvt_pk_bf16_f32 v103, v120, v121
	v_mfma_f32_16x16x32_bf16 v[94:97], v[186:189], v[38:41], v[94:97]
	v_cvt_pk_bf16_f32 v104, v122, v123
	v_cvt_pk_bf16_f32 v105, v124, v105
	v_mfma_f32_16x16x32_bf16 v[38:41], v[216:219], v[38:41], v[42:45]
	s_nop 0
	v_mfma_f32_16x16x32_bf16 v[42:45], v[204:207], v[102:105], v[98:101]
	s_nop 2
	v_exp_f32_e32 v1, v94
	v_exp_f32_e32 v94, v95
	v_exp_f32_e32 v95, v96
	v_exp_f32_e32 v96, v97
	v_exp_f32_e32 v97, v38
	v_exp_f32_e32 v107, v39
	v_exp_f32_e32 v98, v40
	v_exp_f32_e32 v41, v41
	v_mfma_f32_16x16x32_bf16 v[50:53], v[54:57], v[102:105], v[50:53]
	v_cvt_pk_bf16_f32 v38, v1, v94
	v_cvt_pk_bf16_f32 v39, v95, v96
	v_cvt_pk_bf16_f32 v40, v97, v107
	v_cvt_pk_bf16_f32 v41, v98, v41
	v_ashrrev_i32_e32 v107, 31, v106
	s_nop 0
	v_mfma_f32_16x16x32_bf16 v[50:53], v[54:57], v[38:41], v[50:53]
	s_waitcnt vmcnt(7)
	v_lshlrev_b32_e32 v54, 16, v14
	s_nop 5
	v_rcp_f32_e32 v94, v50
	v_mfma_f32_16x16x32_bf16 v[42:45], v[200:203], v[38:41], v[42:45]
	v_and_b32_e32 v55, 0xffff0000, v14
	v_lshlrev_b64 v[50:51], 11, v[106:107]
	v_lshl_add_u64 v[96:97], v[172:173], 0, v[50:51]
	v_mfma_f32_16x16x32_bf16 v[50:53], v[74:77], v[58:61], v[66:69]
	v_lshlrev_b32_e32 v74, 16, v15
	s_nop 2
	v_pk_mul_f32 v[42:43], v[42:43], v[94:95] op_sel_hi:[1,0]
	v_and_b32_e32 v75, 0xffff0000, v15
	v_pk_mul_f32 v[42:43], v[42:43], v[54:55]
	v_mfma_f32_16x16x32_bf16 v[54:57], v[90:93], v[78:81], v[114:117]
	v_mul_f32_e64 v68, v44, v94
	v_mul_f32_e64 v69, v45, v94
	v_cvt_pk_bf16_f32 v66, v42, v43
	v_mfma_f32_16x16x32_bf16 v[42:45], v[208:211], v[102:105], v[54:57]
	v_mfma_f32_16x16x32_bf16 v[42:45], v[220:223], v[38:41], v[42:45]
	s_nop 2
	v_mul_f32_e64 v54, v68, v74
	v_mul_f32_e64 v55, v69, v75
	v_cvt_pk_bf16_f32 v67, v54, v55
	global_store_dwordx2 v[96:97], v[66:67], off offset:1536
	v_mfma_f32_16x16x32_bf16 v[54:57], v[62:65], v[58:61], v[70:73]
	v_mul_f32_e64 v42, v42, v94
	v_mul_f32_e64 v43, v43, v94
	v_pk_mul_f32 v[60:61], v[44:45], v[94:95] op_sel_hi:[1,0]
	s_waitcnt vmcnt(7)
	v_lshlrev_b32_e32 v68, 16, v16
	v_and_b32_e32 v69, 0xffff0000, v16
	v_pk_mul_f32 v[42:43], v[42:43], v[68:69]
	v_lshlrev_b32_e32 v62, 16, v17
	v_and_b32_e32 v63, 0xffff0000, v17
	v_cvt_pk_bf16_f32 v58, v42, v43
	v_mfma_f32_16x16x32_bf16 v[42:45], v[86:89], v[78:81], v[54:57]
	s_nop 2
	v_mul_f32_e64 v54, v60, v62
	v_mul_f32_e64 v55, v61, v63
	v_mfma_f32_16x16x32_bf16 v[50:53], v[82:85], v[78:81], v[50:53]
	v_cvt_pk_bf16_f32 v59, v54, v55
	global_store_dwordx2 v[96:97], v[58:59], off offset:1568
	v_mfma_f32_16x16x32_bf16 v[50:53], v[212:215], v[102:105], v[50:53]
	s_waitcnt vmcnt(7)
	v_lshlrev_b32_e32 v56, 16, v18
	v_mfma_f32_16x16x32_bf16 v[50:53], v[224:227], v[38:41], v[50:53]
	v_and_b32_e32 v57, 0xffff0000, v18
	v_lshlrev_b32_e32 v54, 16, v19
	v_and_b32_e32 v55, 0xffff0000, v19
	v_mfma_f32_16x16x32_bf16 v[42:45], v[110:113], v[102:105], v[42:45]
	v_mfma_f32_16x16x32_bf16 v[38:41], v[46:49], v[38:41], v[42:45]
	s_nop 2
	v_mul_f32_e64 v50, v50, v94
	v_mul_f32_e64 v51, v51, v94
	v_pk_mul_f32 v[52:53], v[52:53], v[94:95] op_sel_hi:[1,0]
	v_pk_mul_f32 v[50:51], v[50:51], v[56:57]
	v_pk_mul_f32 v[52:53], v[52:53], v[54:55]
	v_cvt_pk_bf16_f32 v50, v50, v51
	v_cvt_pk_bf16_f32 v51, v52, v53
	global_store_dwordx2 v[96:97], v[50:51], off offset:1600
	v_pk_mul_f32 v[38:39], v[38:39], v[94:95] op_sel_hi:[1,0]
	v_pk_mul_f32 v[40:41], v[40:41], v[94:95] op_sel_hi:[1,0]
	s_waitcnt vmcnt(7)
	v_lshlrev_b32_e32 v42, 16, v20
	v_and_b32_e32 v43, 0xffff0000, v20
	v_lshlrev_b32_e32 v44, 16, v21
	v_and_b32_e32 v45, 0xffff0000, v21
	v_pk_mul_f32 v[38:39], v[38:39], v[42:43]
	v_pk_mul_f32 v[40:41], v[40:41], v[44:45]
	v_cvt_pk_bf16_f32 v38, v38, v39
	v_cvt_pk_bf16_f32 v39, v40, v41
	global_store_dwordx2 v[96:97], v[38:39], off offset:1632
	s_barrier
	s_cbranch_scc0 .LBB0_467
